# v85 + tile-group barrier polls use s_sleep 0 instead of s_sleep 1
# speedup vs baseline: 1.0026x; 1.0026x over previous
.Lmy_s2_poll:
	global_load_dword v1, v0, s[52:53] sc1
	global_load_dword v3, v2, s[52:53] sc1
	s_waitcnt vmcnt(0)
	v_min_u32_e32 v1, v1, v3
	v_cmp_gt_u32_e32 vcc, 4, v1
	s_cbranch_vccz .Lmy_s2_ready
	s_sleep 0
	s_add_u32 s14, s14, 1
	s_cmp_lt_u32 s14, 0x8000
	s_cbranch_scc1 .Lmy_s2_poll
